# v56 plus gate_up unit loop: next tile is (same row block, column block+4), replacing the per-unit tile-order divisions by two scalar ops
# speedup vs baseline: 1.0017x; 1.0017x over previous
;     __device__ bool next(int i, Unit& u) const { if (i > 0) return false; const int t = c - first; if (t < 0 || t >= nM * nN) return false; u.pm = t % nM; u.pn = t / nM; return true; }
;     __host__ __device__ bool next(int i, Unit& u) const {
;         const long L = (long)i * G + c; if (L >= nwg) return false;
;         int wgid = (int)L; { const int q = nwg / NXCD, r = nwg % NXCD, xcd = wgid % NXCD, off = wgid / NXCD; wgid = (xcd < r ? xcd * (q + 1) : r * (q + 1) + (xcd - r) * q) + off; }
;         const int nig = WGM * nN, gid = wgid / nig, fm = gid * WGM, gsz = (nM - fm) < WGM ? (nM - fm) : WGM;
;         u.pm = fm + ((wgid % nig) % gsz); u.pn = (wgid % nig) / gsz; return true;
;     }
; template <class Epi, class Sched, bool ALIGN_EPI = false, bool SP2 = false>
; __device__ __forceinline__ void gemm_phase(PG8_LAS unsigned char* lds, const Gemm g, const Sched& S, const Epi& E, int tid_in) {
;     ...
;         const bool has_next = S.next(ui + 1, nxt);
;         const char* nA = has_next ? (const char*)g.A + (size_t)nxt.pm * tstep : cA; const char* nB = has_next ? (const char*)g.Bt + (size_t)nxt.pn * tstep : cB;
.LBB0_517:
	s_add_i32 s49, s49, 1
	s_mul_i32 s10, s49, s52
	s_mul_hi_u32 s11, s49, s53
	s_add_i32 s11, s11, s10
	s_mul_i32 s10, s49, s53
	s_add_u32 s26, s10, s2
	s_addc_u32 s27, s11, s31
	v_cmp_gt_i64_e32 vcc, s[26:27], v[144:145]
	v_cmp_lt_i64_e64 s[10:11], s[26:27], v[142:143]
	s_cbranch_vccnz .LBB0_519
	s_add_i32 s22, s57, 4
	s_mov_b32 s24, s36

;     __device__ bool next(int i, Unit& u) const { if (i > 0) return false; const int t = c - first; if (t < 0 || t >= nM * nN) return false; u.pm = t % nM; u.pn = t / nM; return true; }
;     __host__ __device__ bool next(int i, Unit& u) const {
;         const long L = (long)i * G + c; if (L >= nwg) return false;
;         int wgid = (int)L; { const int q = nwg / NXCD, r = nwg % NXCD, xcd = wgid % NXCD, off = wgid / NXCD; wgid = (xcd < r ? xcd * (q + 1) : r * (q + 1) + (xcd - r) * q) + off; }
;         const int nig = WGM * nN, gid = wgid / nig, fm = gid * WGM, gsz = (nM - fm) < WGM ? (nM - fm) : WGM;
;         u.pm = fm + ((wgid % nig) % gsz); u.pn = (wgid % nig) / gsz; return true;
;     }
; template <class Epi, class Sched, bool ALIGN_EPI = false, bool SP2 = false>
; __device__ __forceinline__ void gemm_phase(PG8_LAS unsigned char* lds, const Gemm g, const Sched& S, const Epi& E, int tid_in) {
;     ...
;         const bool has_next = S.next(ui + 1, nxt);
;         const char* nA = has_next ? (const char*)g.A + (size_t)nxt.pm * tstep : cA; const char* nB = has_next ? (const char*)g.Bt + (size_t)nxt.pn * tstep : cB;
.LBB0_993:
	s_add_i32 s61, s61, 1
	s_mul_i32 s4, s61, s64
	s_mul_hi_u32 s5, s61, s65
	s_add_i32 s5, s5, s4
	s_mul_i32 s4, s61, s65
	s_add_u32 s44, s4, s2
	s_addc_u32 s45, s5, s40
	v_cmp_gt_i64_e32 vcc, s[44:45], v[144:145]
	v_cmp_lt_i64_e64 s[16:17], s[44:45], v[142:143]
	s_cbranch_vccnz .LBB0_995
	s_add_i32 s26, s49, 4
	s_mov_b32 s42, s48

;     __device__ bool next(int i, Unit& u) const { if (i > 0) return false; const int t = c - first; if (t < 0 || t >= nM * nN) return false; u.pm = t % nM; u.pn = t / nM; return true; }
;     __host__ __device__ bool next(int i, Unit& u) const {
;         const long L = (long)i * G + c; if (L >= nwg) return false;
;         int wgid = (int)L; { const int q = nwg / NXCD, r = nwg % NXCD, xcd = wgid % NXCD, off = wgid / NXCD; wgid = (xcd < r ? xcd * (q + 1) : r * (q + 1) + (xcd - r) * q) + off; }
;         const int nig = WGM * nN, gid = wgid / nig, fm = gid * WGM, gsz = (nM - fm) < WGM ? (nM - fm) : WGM;
;         u.pm = fm + ((wgid % nig) % gsz); u.pn = (wgid % nig) / gsz; return true;
;     }
; template <class Epi, class Sched, bool ALIGN_EPI = false, bool SP2 = false>
; __device__ __forceinline__ void gemm_phase(PG8_LAS unsigned char* lds, const Gemm g, const Sched& S, const Epi& E, int tid_in) {
;     ...
;         const bool has_next = S.next(ui + 1, nxt);
;         const char* nA = has_next ? (const char*)g.A + (size_t)nxt.pm * tstep : cA; const char* nB = has_next ? (const char*)g.Bt + (size_t)nxt.pn * tstep : cB;
.LBB0_1585:
	s_add_i32 s53, s53, 1
	s_mul_i32 s4, s53, s56
	s_mul_hi_u32 s5, s53, s57
	s_add_i32 s5, s5, s4
	s_mul_i32 s4, s53, s57
	s_add_u32 s26, s4, s2
	s_addc_u32 s27, s5, s13
	v_cmp_gt_i64_e32 vcc, s[26:27], v[144:145]
	v_cmp_lt_i64_e64 s[8:9], s[26:27], v[142:143]
	s_cbranch_vccnz .LBB0_1587
	s_add_i32 s22, s61, 4
	s_mov_b32 s24, s44

;     __device__ bool next(int i, Unit& u) const { if (i > 0) return false; const int t = c - first; if (t < 0 || t >= nM * nN) return false; u.pm = t % nM; u.pn = t / nM; return true; }
;     __host__ __device__ bool next(int i, Unit& u) const {
;         const long L = (long)i * G + c; if (L >= nwg) return false;
;         int wgid = (int)L; { const int q = nwg / NXCD, r = nwg % NXCD, xcd = wgid % NXCD, off = wgid / NXCD; wgid = (xcd < r ? xcd * (q + 1) : r * (q + 1) + (xcd - r) * q) + off; }
;         const int nig = WGM * nN, gid = wgid / nig, fm = gid * WGM, gsz = (nM - fm) < WGM ? (nM - fm) : WGM;
;         u.pm = fm + ((wgid % nig) % gsz); u.pn = (wgid % nig) / gsz; return true;
;     }
; template <class Epi, class Sched, bool ALIGN_EPI = false, bool SP2 = false>
; __device__ __forceinline__ void gemm_phase(PG8_LAS unsigned char* lds, const Gemm g, const Sched& S, const Epi& E, int tid_in) {
;     ...
;         const bool has_next = S.next(ui + 1, nxt);
;         const char* nA = has_next ? (const char*)g.A + (size_t)nxt.pm * tstep : cA; const char* nB = has_next ? (const char*)g.Bt + (size_t)nxt.pn * tstep : cB;
.LBB0_2037:
	s_add_i32 s40, s40, 1
	s_mul_i32 s6, s40, s43
	s_mul_hi_u32 s7, s40, s44
	s_add_i32 s7, s7, s6
	s_mul_i32 s6, s40, s44
	s_add_u32 s20, s6, s2
	s_addc_u32 s21, s7, s30
	v_cmp_gt_i64_e32 vcc, s[20:21], v[144:145]
	v_cmp_lt_i64_e64 s[6:7], s[20:21], v[142:143]
	s_cbranch_vccnz .LBB0_2039
	s_add_i32 s16, s48, 4
	s_mov_b32 s18, s24
